# NSA selected sweep interior tile rewritten in place: no accumulator copies, both halves QK issued up front, V fragments prefetched
# speedup vs baseline: 1.1243x; 1.0077x over previous
.LBB0_283:
	s_add_i32 s13, s12, 1
	s_min_i32 s4, s13, s10
	s_lshl_b32 s96, s4, 6
	v_add_u32_e32 v2, s96, v158
	v_add_u32_e32 v4, s96, v160
	v_ashrrev_i32_e32 v3, 31, v2
	v_ashrrev_i32_e32 v5, 31, v4
	v_lshlrev_b64 v[2:3], 7, v[2:3]
	v_lshlrev_b64 v[4:5], 7, v[4:5]
	v_lshl_add_u64 v[2:3], v[170:171], 0, v[2:3]
	v_lshl_add_u64 v[4:5], v[170:171], 0, v[4:5]
	s_lshl_b64 s[4:5], s[96:97], 1
	global_load_dwordx4 v[8:11], v[2:3], off
	s_nop 0
	global_load_dwordx4 v[4:7], v[4:5], off
	v_lshl_add_u64 v[2:3], v[162:163], 0, s[4:5]
	v_lshl_add_u64 v[48:49], v[164:165], 0, s[4:5]
	global_load_dwordx4 v[12:15], v[2:3], off
	global_load_dwordx4 v[112:115], v[48:49], off
	s_and_b32 s14, s12, 1
	s_mul_i32 s4, s14, 0x4800
	v_lshrrev_b64 v[2:3], s12, v[128:129]
	s_lshl_b32 s15, s12, 6
	v_and_b32_e32 v0, 1, v2
	s_or_b32 s5, s15, 63
	v_or_b32_e32 v3, s4, v131
	v_cmp_eq_u64_e64 s[38:39], 0, v[0:1]
	s_cmp_gt_i32 s5, s8
	v_add_u32_e32 v172, v3, v161
	s_mov_b64 s[4:5], -1
	s_cbranch_scc1 .LBB0_289
	v_mad_u32_u24 v0, v116, s37, v3
	v_lshl_add_u32 v215, v156, 1, v172
	ds_read_b128 v[220:223], v0
	ds_read_b128 v[236:239], v0 offset:4608
	ds_read_b128 v[224:227], v0 offset:32
	ds_read_b128 v[240:243], v0 offset:4640
	ds_read_b128 v[228:231], v0 offset:64
	ds_read_b128 v[244:247], v0 offset:4672
	ds_read_b128 v[232:235], v0 offset:96
	ds_read_b128 v[248:251], v0 offset:4704
	v_add_u32_e32 v214, 0x3000, v215
	v_add_u32_e32 v215, 0x2000, v215
	ds_read2_b64 v[64:67], v215 offset0:128 offset1:130
	ds_read2_b64 v[68:71], v214 offset0:192 offset1:194
	ds_read2_b64 v[72:75], v215 offset0:132 offset1:134
	ds_read2_b64 v[76:79], v214 offset0:196 offset1:198
	s_waitcnt lgkmcnt(11)
	v_mfma_f32_32x32x16_bf16 v[80:95], v[220:223], v[96:99], 0
	s_waitcnt lgkmcnt(10)
	v_mfma_f32_32x32x16_bf16 v[48:63], v[236:239], v[96:99], 0
	s_waitcnt lgkmcnt(9)
	v_mfma_f32_32x32x16_bf16 v[80:95], v[224:227], v[100:103], v[80:95]
	s_waitcnt lgkmcnt(8)
	v_mfma_f32_32x32x16_bf16 v[48:63], v[240:243], v[100:103], v[48:63]
	s_waitcnt lgkmcnt(7)
	v_mfma_f32_32x32x16_bf16 v[80:95], v[228:231], v[104:107], v[80:95]
	s_waitcnt lgkmcnt(6)
	v_mfma_f32_32x32x16_bf16 v[48:63], v[244:247], v[104:107], v[48:63]
	s_waitcnt lgkmcnt(5)
	v_mfma_f32_32x32x16_bf16 v[80:95], v[232:235], v[108:111], v[80:95]
	s_waitcnt lgkmcnt(4)
	v_mfma_f32_32x32x16_bf16 v[48:63], v[248:251], v[108:111], v[48:63]
	ds_read2_b64 v[220:223], v215 offset0:136 offset1:138
	ds_read2_b64 v[224:227], v214 offset0:200 offset1:202
	ds_read2_b64 v[228:231], v215 offset0:140 offset1:142
	ds_read2_b64 v[232:235], v214 offset0:204 offset1:206
	s_nop 7
	v_max3_f32 v0, v80, v81, v82
	v_max3_f32 v2, v88, v89, v90
	v_max3_f32 v0, v0, v83, v84
	v_max3_f32 v2, v2, v91, v92
	v_max3_f32 v0, v0, v85, v86
	v_max3_f32 v2, v2, v93, v94
	v_max3_f32 v0, v0, v87, v95
	v_max_f32_e32 v0, v0, v2
	v_cndmask_b32_e64 v0, v0, v202, s[38:39]
	ds_bpermute_b32 v2, v119, v0
	s_waitcnt lgkmcnt(0)
	v_max3_f32 v173, v167, v0, v2
	v_sub_f32_e32 v0, v167, v173
	v_exp_f32_e32 v0, v0
	v_cmp_eq_f32_e32 vcc, v173, v167
	s_cmp_eq_u64 vcc, exec
	s_cbranch_scc1 .Lnsw_keep0
	v_pk_mul_f32 v[46:47], v[46:47], v[0:1] op_sel_hi:[1,0]
	v_pk_mul_f32 v[44:45], v[44:45], v[0:1] op_sel_hi:[1,0]
	v_pk_mul_f32 v[42:43], v[42:43], v[0:1] op_sel_hi:[1,0]
	v_pk_mul_f32 v[40:41], v[40:41], v[0:1] op_sel_hi:[1,0]
	v_pk_mul_f32 v[38:39], v[38:39], v[0:1] op_sel_hi:[1,0]
	v_pk_mul_f32 v[36:37], v[36:37], v[0:1] op_sel_hi:[1,0]
	v_pk_mul_f32 v[34:35], v[34:35], v[0:1] op_sel_hi:[1,0]
	v_pk_mul_f32 v[32:33], v[32:33], v[0:1] op_sel_hi:[1,0]
	v_pk_mul_f32 v[30:31], v[30:31], v[0:1] op_sel_hi:[1,0]
	v_pk_mul_f32 v[28:29], v[28:29], v[0:1] op_sel_hi:[1,0]
	v_pk_mul_f32 v[26:27], v[26:27], v[0:1] op_sel_hi:[1,0]
	v_pk_mul_f32 v[24:25], v[24:25], v[0:1] op_sel_hi:[1,0]
	v_pk_mul_f32 v[22:23], v[22:23], v[0:1] op_sel_hi:[1,0]
	v_pk_mul_f32 v[20:21], v[20:21], v[0:1] op_sel_hi:[1,0]
	v_pk_mul_f32 v[18:19], v[18:19], v[0:1] op_sel_hi:[1,0]
	v_pk_mul_f32 v[16:17], v[16:17], v[0:1] op_sel_hi:[1,0]
.Lnsw_keep0:
	v_mov_b32_e32 v167, v173
	v_cndmask_b32_e64 v174, v173, v206, s[38:39]
	v_sub_f32_e32 v80, v80, v174
	v_exp_f32_e32 v80, v80
	v_sub_f32_e32 v81, v81, v174
	v_exp_f32_e32 v81, v81
	v_add_f32_e32 v175, 0, v80
	v_sub_f32_e32 v82, v82, v174
	v_exp_f32_e32 v82, v82
	v_add_f32_e32 v175, v81, v175
	v_sub_f32_e32 v83, v83, v174
	v_exp_f32_e32 v83, v83
	v_add_f32_e32 v175, v82, v175
	v_cvt_pk_bf16_f32 v176, v80, v81
	v_sub_f32_e32 v84, v84, v174
	v_exp_f32_e32 v84, v84
	v_add_f32_e32 v175, v83, v175
	v_sub_f32_e32 v85, v85, v174
	v_exp_f32_e32 v85, v85
	v_add_f32_e32 v175, v84, v175
	v_cvt_pk_bf16_f32 v177, v82, v83
	v_sub_f32_e32 v86, v86, v174
	v_exp_f32_e32 v86, v86
	v_add_f32_e32 v175, v85, v175
	v_sub_f32_e32 v87, v87, v174
	v_exp_f32_e32 v87, v87
	v_add_f32_e32 v175, v86, v175
	v_cvt_pk_bf16_f32 v178, v84, v85
	v_sub_f32_e32 v88, v88, v174
	v_exp_f32_e32 v88, v88
	v_add_f32_e32 v175, v87, v175
	v_sub_f32_e32 v89, v89, v174
	v_exp_f32_e32 v89, v89
	v_add_f32_e32 v175, v88, v175
	v_cvt_pk_bf16_f32 v179, v86, v87
	v_sub_f32_e32 v90, v90, v174
	v_exp_f32_e32 v90, v90
	v_add_f32_e32 v175, v89, v175
	v_mfma_f32_32x32x16_bf16 v[32:47], v[64:67], v[176:179], v[32:47]
	v_mfma_f32_32x32x16_bf16 v[16:31], v[68:71], v[176:179], v[16:31]
	v_sub_f32_e32 v91, v91, v174
	v_exp_f32_e32 v91, v91
	v_add_f32_e32 v175, v90, v175
	v_cvt_pk_bf16_f32 v180, v88, v89
	v_sub_f32_e32 v92, v92, v174
	v_exp_f32_e32 v92, v92
	v_add_f32_e32 v175, v91, v175
	v_sub_f32_e32 v93, v93, v174
	v_exp_f32_e32 v93, v93
	v_add_f32_e32 v175, v92, v175
	v_cvt_pk_bf16_f32 v181, v90, v91
	v_sub_f32_e32 v94, v94, v174
	v_exp_f32_e32 v94, v94
	v_add_f32_e32 v175, v93, v175
	v_sub_f32_e32 v95, v95, v174
	v_exp_f32_e32 v95, v95
	v_add_f32_e32 v175, v94, v175
	v_cvt_pk_bf16_f32 v182, v92, v93
	v_add_f32_e32 v175, v95, v175
	v_cvt_pk_bf16_f32 v183, v94, v95
	v_fmac_f32_e32 v175, v169, v0
	v_mov_b32_e32 v169, v175
	s_nop 0
	v_mfma_f32_32x32x16_bf16 v[32:47], v[72:75], v[180:183], v[32:47]
	v_mfma_f32_32x32x16_bf16 v[16:31], v[76:79], v[180:183], v[16:31]
	v_max3_f32 v0, v48, v49, v50
	v_max3_f32 v2, v56, v57, v58
	v_max3_f32 v0, v0, v51, v52
	v_max3_f32 v2, v2, v59, v60
	v_max3_f32 v0, v0, v53, v54
	v_max3_f32 v2, v2, v61, v62
	v_max3_f32 v0, v0, v55, v63
	v_max_f32_e32 v0, v0, v2
	v_cndmask_b32_e64 v0, v0, v202, s[38:39]
	ds_bpermute_b32 v2, v119, v0
	s_waitcnt lgkmcnt(0)
	v_max3_f32 v173, v167, v0, v2
	v_sub_f32_e32 v0, v167, v173
	v_exp_f32_e32 v0, v0
	v_cmp_eq_f32_e32 vcc, v173, v167
	s_cmp_eq_u64 vcc, exec
	s_cbranch_scc1 .Lnsw_keep1
	v_pk_mul_f32 v[46:47], v[46:47], v[0:1] op_sel_hi:[1,0]
	v_pk_mul_f32 v[44:45], v[44:45], v[0:1] op_sel_hi:[1,0]
	v_pk_mul_f32 v[42:43], v[42:43], v[0:1] op_sel_hi:[1,0]
	v_pk_mul_f32 v[40:41], v[40:41], v[0:1] op_sel_hi:[1,0]
	v_pk_mul_f32 v[38:39], v[38:39], v[0:1] op_sel_hi:[1,0]
	v_pk_mul_f32 v[36:37], v[36:37], v[0:1] op_sel_hi:[1,0]
	v_pk_mul_f32 v[34:35], v[34:35], v[0:1] op_sel_hi:[1,0]
	v_pk_mul_f32 v[32:33], v[32:33], v[0:1] op_sel_hi:[1,0]
	v_pk_mul_f32 v[30:31], v[30:31], v[0:1] op_sel_hi:[1,0]
	v_pk_mul_f32 v[28:29], v[28:29], v[0:1] op_sel_hi:[1,0]
	v_pk_mul_f32 v[26:27], v[26:27], v[0:1] op_sel_hi:[1,0]
	v_pk_mul_f32 v[24:25], v[24:25], v[0:1] op_sel_hi:[1,0]
	v_pk_mul_f32 v[22:23], v[22:23], v[0:1] op_sel_hi:[1,0]
	v_pk_mul_f32 v[20:21], v[20:21], v[0:1] op_sel_hi:[1,0]
	v_pk_mul_f32 v[18:19], v[18:19], v[0:1] op_sel_hi:[1,0]
	v_pk_mul_f32 v[16:17], v[16:17], v[0:1] op_sel_hi:[1,0]
.Lnsw_keep1:
	v_mov_b32_e32 v167, v173
	v_cndmask_b32_e64 v174, v173, v206, s[38:39]
	v_sub_f32_e32 v48, v48, v174
	v_exp_f32_e32 v48, v48
	v_sub_f32_e32 v49, v49, v174
	v_exp_f32_e32 v49, v49
	v_add_f32_e32 v175, 0, v48
	v_sub_f32_e32 v50, v50, v174
	v_exp_f32_e32 v50, v50
	v_add_f32_e32 v175, v49, v175
	v_sub_f32_e32 v51, v51, v174
	v_exp_f32_e32 v51, v51
	v_add_f32_e32 v175, v50, v175
	v_cvt_pk_bf16_f32 v80, v48, v49
	v_sub_f32_e32 v52, v52, v174
	v_exp_f32_e32 v52, v52
	v_add_f32_e32 v175, v51, v175
	v_sub_f32_e32 v53, v53, v174
	v_exp_f32_e32 v53, v53
	v_add_f32_e32 v175, v52, v175
	v_cvt_pk_bf16_f32 v81, v50, v51
	v_sub_f32_e32 v54, v54, v174
	v_exp_f32_e32 v54, v54
	v_add_f32_e32 v175, v53, v175
	v_sub_f32_e32 v55, v55, v174
	v_exp_f32_e32 v55, v55
	v_add_f32_e32 v175, v54, v175
	v_cvt_pk_bf16_f32 v82, v52, v53
	v_sub_f32_e32 v56, v56, v174
	v_exp_f32_e32 v56, v56
	v_add_f32_e32 v175, v55, v175
	v_sub_f32_e32 v57, v57, v174
	v_exp_f32_e32 v57, v57
	v_add_f32_e32 v175, v56, v175
	v_cvt_pk_bf16_f32 v83, v54, v55
	v_sub_f32_e32 v58, v58, v174
	v_exp_f32_e32 v58, v58
	v_add_f32_e32 v175, v57, v175
	v_mfma_f32_32x32x16_bf16 v[32:47], v[220:223], v[80:83], v[32:47]
	v_mfma_f32_32x32x16_bf16 v[16:31], v[224:227], v[80:83], v[16:31]
	v_sub_f32_e32 v59, v59, v174
	v_exp_f32_e32 v59, v59
	v_add_f32_e32 v175, v58, v175
	v_cvt_pk_bf16_f32 v84, v56, v57
	v_sub_f32_e32 v60, v60, v174
	v_exp_f32_e32 v60, v60
	v_add_f32_e32 v175, v59, v175
	v_sub_f32_e32 v61, v61, v174
	v_exp_f32_e32 v61, v61
	v_add_f32_e32 v175, v60, v175
	v_cvt_pk_bf16_f32 v85, v58, v59
	v_sub_f32_e32 v62, v62, v174
	v_exp_f32_e32 v62, v62
	v_add_f32_e32 v175, v61, v175
	v_sub_f32_e32 v63, v63, v174
	v_exp_f32_e32 v63, v63
	v_add_f32_e32 v175, v62, v175
	v_cvt_pk_bf16_f32 v86, v60, v61
	v_add_f32_e32 v175, v63, v175
	v_cvt_pk_bf16_f32 v87, v62, v63
	v_fmac_f32_e32 v175, v169, v0
	v_mov_b32_e32 v169, v175
	s_nop 0
	v_mfma_f32_32x32x16_bf16 v[32:47], v[228:231], v[84:87], v[32:47]
	v_mfma_f32_32x32x16_bf16 v[16:31], v[232:235], v[84:87], v[16:31]
	s_branch .LBB0_296

.LBB0_295:
	v_mov_b32_e32 v169, v2
.LBB0_296:
	s_xor_b32 s4, s14, 1
	s_mulk_i32 s4, 0x4800
	v_lshl_add_u32 v0, v166, 1, s4
	v_lshl_add_u32 v3, v168, 1, s4
	s_cmp_lg_u32 s12, s10
	s_waitcnt vmcnt(3)
	ds_write_b128 v0, v[8:11]
	s_waitcnt vmcnt(2)
	ds_write_b128 v3, v[4:7]
	s_waitcnt vmcnt(1)
	ds_write_b128 v0, v[12:15] offset:9216
	s_waitcnt vmcnt(0)
	ds_write_b128 v3, v[112:115] offset:9216
	s_waitcnt lgkmcnt(0)
	s_barrier
	s_cbranch_scc0 .Lnsw_exit
	s_mov_b32 s12, s13
	s_branch .LBB0_283
.Lnsw_exit:
	s_nop 7
	s_nop 7
	v_mov_b64_e32 v[48:49], v[16:17]
	v_mov_b64_e32 v[50:51], v[18:19]
	v_mov_b64_e32 v[52:53], v[20:21]
	v_mov_b64_e32 v[54:55], v[22:23]
	v_mov_b64_e32 v[56:57], v[24:25]
	v_mov_b64_e32 v[58:59], v[26:27]
	v_mov_b64_e32 v[60:61], v[28:29]
	v_mov_b64_e32 v[62:63], v[30:31]
	v_mov_b64_e32 v[64:65], v[32:33]
	v_mov_b64_e32 v[66:67], v[34:35]
	v_mov_b64_e32 v[68:69], v[36:37]
	v_mov_b64_e32 v[70:71], v[38:39]
	v_mov_b64_e32 v[72:73], v[40:41]
	v_mov_b64_e32 v[74:75], v[42:43]
	v_mov_b64_e32 v[76:77], v[44:45]
	v_mov_b64_e32 v[78:79], v[46:47]
	v_mov_b32_e32 v173, v167
	v_mov_b32_e32 v2, v169
	s_branch .LBB0_299
